# rec chunk loop: batched LDS fragment reads + permlane reductions, plus task-contiguous o layout for the recurrence output / head norm
# baseline (speedup 1.0000x reference)
; __device__ __forceinline__ int tidx() { int t = threadIdx.x; asm volatile("" : "+v"(t)); return t; }
; #define LAS __attribute__((address_space(3)))
; __device__ __forceinline__ void rec_loop_task(const P& p, unsigned char* ws, int l, LAS unsigned char* lds, int tk) {
;     const int tid = tidx(), lane = tid & 63, w = __builtin_amdgcn_readfirstlane(tid >> 6), fr = lane & 15, fq = lane >> 4;
;     const int xcd = tk & 7, jx = tk >> 3;
;     const bool gla = jx >= 8;
;     const int sh = gla ? xcd + 8 * ((jx - 8) >> 2) : xcd + 8 * (jx >> 1), vs = gla ? ((jx - 8) & 3) : (jx & 1), V = gla ? GV : HV, nheads = gla ? GH : HH, b = sh / nheads, head = sh % nheads;
;     const int shg = gla ? sh + BATCH * HH : sh;
;     const unsigned char* img0 = ws + WS_IMG + (size_t)shg * 32 * IMG_BYTES;
;     const float* em0 = (const float*)(ws + WS_EMID) + (size_t)shg * 32 * 128 + (w >> 1) * 32 + fq * 4;
;     const bf16_t* vp = (const bf16_t*)(ws + (gla ? WS_VG : WS_VH)) + (size_t)(b * SEQ) * 1024 + head * V + vs * 64;
;     float* op = (float*)(ws + WS_T32) + (size_t)(b * SEQ) * D + (gla ? 1024 : 0) + head * V + vs * 64;
;     float* sp = p.out + (gla ? OUT_GP : OUT_HP) + (size_t)l * BATCH * nheads * 128 * V + ((size_t)sh * 128) * V + vs * 64;
;     const int ti = w >> 1, vi = w & 1;
;     f32x4 Sacc[2][2];
; #pragma unroll
;     for (int cj = 0; cj < 2; ++cj)
; #pragma unroll
;         for (int oj = 0; oj < 2; ++oj) Sacc[cj][oj] = (f32x4){0.f, 0.f, 0.f, 0.f};
;     __syncthreads();
;     for (int i = tid; i < 64 * SQ / 4; i += NTHR) ((LAS unsigned*)(lds + R_ST0))[i] = 0u;
;     constexpr int NCORE = IMG_BYTES / 16;
;     u32x4 pre[7], pre2[7]; f32x4 em1[2], em2[2];
;     int pidx[6];
; #pragma unroll
;     for (int i = 0; i < 6; ++i) { const int pi_ = tid + i * NTHR; pidx[i] = pi_ < NCORE ? pi_ : NCORE - 1; }
;     const int vt_t = ((tid >> 6) & 1) * 32 + (tid & 31), vt_q = (tid >> 7) * 2 + ((tid >> 5) & 1);
;     ...
;     REC_FETCH(pre, em1, 0); REC_FETCH(pre2, em2, 1);
.LBB0_1086:
	s_or_b64 exec, exec, s[0:1]
	v_cvt_f32_ubyte0_e32 v2, s35
	v_rcp_iflag_f32_e32 v2, v2
	s_sub_i32 s21, 0, s35
	s_and_b32 s0, s45, 7
	s_or_b32 s78, s25, s0
	v_mul_f32_e32 v2, 0x4f7ffffe, v2
	v_cvt_u32_f32_e32 v2, v2
	s_abs_i32 s1, s78
	s_and_b32 s77, s26, s24
	s_ashr_i32 s0, s25, 31
	v_readfirstlane_b32 s22, v2
	s_mul_i32 s21, s21, s22
	s_mul_hi_u32 s21, s22, s21
	s_add_i32 s22, s22, s21
	s_mul_hi_u32 s21, s1, s22
	s_mul_i32 s22, s21, s35
	s_sub_i32 s1, s1, s22
	s_add_i32 s22, s21, 1
	s_sub_i32 s23, s1, s35
	s_cmp_ge_u32 s1, s35
	s_cselect_b32 s21, s22, s21
	s_cselect_b32 s1, s23, s1
	s_add_i32 s22, s21, 1
	s_cmp_ge_u32 s1, s35
	s_cselect_b32 s1, s22, s21
	s_xor_b32 s1, s1, s0
	s_sub_i32 s21, s1, s0
	s_mul_i32 s0, s21, s35
	s_sub_i32 s24, s78, s0
	s_add_i32 s22, s78, 32
	s_and_b64 s[0:1], s[36:37], exec
	s_cselect_b32 s0, s22, s78
	s_ashr_i32 s1, s0, 31
	s_lshl_b64 s[22:23], s[0:1], 14
	s_add_u32 s25, s60, s22
	s_addc_u32 s26, s61, s23
	s_ashr_i32 s81, s75, 1
	s_lshl_b32 s22, s81, 5
	s_ashr_i32 s23, s22, 31
	s_lshl_b64 s[22:23], s[22:23], 2
	s_add_u32 s40, s25, s22
	s_addc_u32 s41, s26, s23
	s_lshl_b32 s28, s21, 11
	s_ashr_i32 s29, s28, 31
	s_mul_i32 s30, s24, s76
	s_ashr_i32 s31, s30, 31
	s_lshl_b32 s79, s77, 6
	s_lshl_b64 s[26:27], s[28:29], 11
	s_lshl_b64 s[22:23], s[28:29], 13
	s_add_u32 s24, s62, s22
	s_addc_u32 s25, s63, s23
	s_lshl_b32 s21, s20, 2
	s_add_u32 s42, s24, s21
	s_addc_u32 s43, s25, 0
	s_lshl_b64 s[24:25], s[30:31], 2
	s_add_u32 s80, s42, s24
	s_mul_i32 s38, s0, 0x164000
	s_addc_u32 s92, s43, s25
	s_mul_hi_i32 s39, s0, 0x164000
	s_add_u32 s38, s66, s38
	s_addc_u32 s39, s67, s39
	s_add_u32 s6, s12, s6
	s_addc_u32 s7, s13, s7
	s_add_u32 s6, s6, s26
	v_min_i32_e32 v2, 0x91f, v107
	s_addc_u32 s7, s7, s27
	s_lshl_b64 s[30:31], s[30:31], 1
	v_add_u32_e32 v68, 0x200, v2
	v_min_i32_e32 v2, 0x71f, v107
	s_add_u32 s6, s6, s30
	v_add_u32_e32 v70, 0x400, v2
	v_min_i32_e32 v2, 0x51f, v107
	s_addc_u32 s7, s7, s31
	s_lshl_b32 s74, s77, 7
	v_min_i32_e32 v66, 0xb1f, v107
	v_add_u32_e32 v72, 0x600, v2
	v_min_i32_e32 v2, 0x31f, v107
	s_add_u32 s42, s6, s74
	v_add_u32_e32 v82, 0x800, v2
	v_min_i32_e32 v2, 0x11f, v107
	v_lshrrev_b32_e32 v27, 5, v107
	v_ashrrev_i32_e32 v67, 31, v66
	s_addc_u32 s43, s7, 0
	s_lshl_b32 s73, s77, 8
	v_add_u32_e32 v84, 0xa00, v2
	v_lshlrev_b32_e32 v2, 5, v26
	v_and_b32_e32 v3, 31, v107
	v_lshlrev_b64 v[112:113], 4, v[66:67]
	v_bfi_b32 v67, -2, v26, v27
	s_add_u32 s6, s80, s73
	v_and_or_b32 v89, v2, 32, v3
	v_lshlrev_b32_e32 v28, 3, v67
	s_addc_u32 s7, s92, 0
	s_and_b32 s82, s75, 1
	v_ashrrev_i32_e32 v69, 31, v68
	v_ashrrev_i32_e32 v71, 31, v70
	v_ashrrev_i32_e32 v73, 31, v72
	v_ashrrev_i32_e32 v83, 31, v82
	v_ashrrev_i32_e32 v85, 31, v84
	v_lshlrev_b32_e32 v172, 11, v89
	v_ashrrev_i32_e32 v29, 31, v28
	v_lshlrev_b64 v[114:115], 4, v[68:69]
	v_lshlrev_b64 v[116:117], 4, v[70:71]
	v_lshlrev_b64 v[118:119], 4, v[72:73]
	v_lshlrev_b64 v[120:121], 4, v[82:83]
	v_lshlrev_b64 v[122:123], 4, v[84:85]
	v_lshl_add_u64 v[26:27], s[42:43], 0, v[172:173]
	v_lshlrev_b64 v[86:87], 1, v[28:29]
	s_add_u32 vcc_lo, s38, 0xb200
	v_lshl_add_u64 v[2:3], s[38:39], 0, v[112:113]
	v_lshl_add_u64 v[6:7], s[38:39], 0, v[114:115]
	v_lshl_add_u64 v[10:11], s[38:39], 0, v[116:117]
	v_lshl_add_u64 v[14:15], s[38:39], 0, v[118:119]
	v_lshl_add_u64 v[18:19], s[38:39], 0, v[120:121]
	v_lshl_add_u64 v[22:23], s[38:39], 0, v[122:123]
	v_lshl_add_u64 v[46:47], v[26:27], 0, v[86:87]
	s_addc_u32 vcc_hi, s39, 0
	v_and_b32_e32 v108, 48, v107
	global_load_dwordx4 v[2:5], v[2:3], off
	s_nop 0
	global_load_dwordx4 v[6:9], v[6:7], off
	s_nop 0
	global_load_dwordx4 v[10:13], v[10:11], off
	s_nop 0
	global_load_dwordx4 v[14:17], v[14:15], off
	s_nop 0
	global_load_dwordx4 v[18:21], v[18:19], off
	s_nop 0
	global_load_dwordx4 v[22:25], v[22:23], off
	s_nop 0
	global_load_dwordx4 v[26:29], v[46:47], off
	global_load_dwordx4 v[78:81], v108, s[40:41] offset:512
	global_load_dwordx4 v[74:77], v108, s[40:41] offset:576
	v_lshl_add_u64 v[30:31], vcc, 0, v[112:113]
	v_lshl_add_u64 v[34:35], vcc, 0, v[114:115]
	v_lshl_add_u64 v[38:39], vcc, 0, v[116:117]
	v_lshl_add_u64 v[42:43], vcc, 0, v[118:119]
	v_lshl_add_u64 v[48:49], vcc, 0, v[120:121]
; #define LAS __attribute__((address_space(3)))
; __device__ __forceinline__ void rec_loop_task(const P& p, unsigned char* ws, int l, LAS unsigned char* lds, int tk) {
;     ...
;     const float* em0 = (const float*)(ws + WS_EMID) + (size_t)shg * 32 * 128 + (w >> 1) * 32 + fq * 4;
;     const bf16_t* vp = (const bf16_t*)(ws + (gla ? WS_VG : WS_VH)) + (size_t)(b * SEQ) * 1024 + head * V + vs * 64;
;     float* op = (float*)(ws + WS_T32) + (size_t)(b * SEQ) * D + (gla ? 1024 : 0) + head * V + vs * 64;
;     float* sp = p.out + (gla ? OUT_GP : OUT_HP) + (size_t)l * BATCH * nheads * 128 * V + ((size_t)sh * 128) * V + vs * 64;
;     const int ti = w >> 1, vi = w & 1;
;     f32x4 Sacc[2][2];
; #pragma unroll
;     for (int cj = 0; cj < 2; ++cj)
; #pragma unroll
;         for (int oj = 0; oj < 2; ++oj) Sacc[cj][oj] = (f32x4){0.f, 0.f, 0.f, 0.f};
;     __syncthreads();
;     for (int i = tid; i < 64 * SQ / 4; i += NTHR) ((LAS unsigned*)(lds + R_ST0))[i] = 0u;
;     constexpr int NCORE = IMG_BYTES / 16;
;     u32x4 pre[7], pre2[7]; f32x4 em1[2], em2[2];
;     int pidx[6];
; #pragma unroll
;     for (int i = 0; i < 6; ++i) { const int pi_ = tid + i * NTHR; pidx[i] = pi_ < NCORE ? pi_ : NCORE - 1; }
;     const int vt_t = ((tid >> 6) & 1) * 32 + (tid & 31), vt_q = (tid >> 7) * 2 + ((tid >> 5) & 1);
	v_lshl_add_u64 v[54:55], vcc, 0, v[122:123]
	v_add_co_u32_e32 v46, vcc, s83, v46
	global_load_dwordx4 v[30:33], v[30:31], off
	s_nop 0
	global_load_dwordx4 v[34:37], v[34:35], off
	v_addc_co_u32_e32 v47, vcc, 0, v47, vcc
	global_load_dwordx4 v[38:41], v[38:39], off
	s_nop 0
	global_load_dwordx4 v[42:45], v[42:43], off
	s_nop 0
	global_load_dwordx4 v[50:53], v[48:49], off
	s_nop 0
	global_load_dwordx4 v[54:57], v[54:55], off
	s_nop 0
	global_load_dwordx4 v[46:49], v[46:47], off
	s_nop 0
	global_load_dwordx4 v[62:65], v108, s[40:41] offset:1024
	global_load_dwordx4 v[58:61], v108, s[40:41] offset:1088
	v_and_b32_e32 v85, 64, v215
	v_xor_b32_e32 v83, 16, v215
	v_add_u32_e32 v85, 64, v85
	v_cmp_lt_i32_e32 vcc, v83, v85
	v_mov_b32_e32 v109, v173
	v_bfe_u32 v88, v107, 4, 2
	v_cndmask_b32_e32 v83, v215, v83, vcc
	v_lshlrev_b32_e32 v134, 2, v83
	v_xor_b32_e32 v83, 32, v215
	v_lshl_add_u64 v[110:111], s[40:41], 0, v[108:109]
	v_and_b32_e32 v130, 15, v107
	v_lshl_add_u64 v[124:125], s[42:43], 0, v[86:87]
	s_sub_u32 vcc_lo, s6, s62
	s_and_b32 vcc_hi, vcc_lo, 0x1fff
	s_sub_u32 vcc_lo, vcc_lo, vcc_hi
	s_lshl_b32 vcc_hi, vcc_hi, 11
	s_add_u32 vcc_lo, vcc_lo, vcc_hi
	s_add_u32 s6, s62, vcc_lo
	s_addc_u32 s7, s63, 0
	v_lshl_add_u64 v[86:87], s[6:7], 0, v[108:109]
	v_cmp_lt_i32_e32 vcc, v83, v85
	s_movk_i32 s6, 0x480
	s_lshl_b32 s40, s75, 4
	v_lshlrev_b32_e32 v106, 2, v88
	v_lshl_or_b32 v126, s81, 4, v130
	s_movk_i32 s2, 0x110
	v_cndmask_b32_e32 v83, v215, v83, vcc
	v_mul_lo_u32 v67, v67, s6
	s_and_b32 s6, s40, 0xffffffe0
	v_mul_lo_u32 v71, v126, s2
	v_lshlrev_b32_e32 v135, 2, v83
	v_lshl_add_u32 v83, v88, 3, 0
	v_lshlrev_b32_e32 v88, 4, v82
	v_or_b32_e32 v109, s6, v106
	v_or_b32_e32 v82, s6, v130
	s_movk_i32 s2, 0x90
	s_or_b32 s6, s40, 16
	v_mul_lo_u32 v90, v82, s2
	v_or_b32_e32 v82, s6, v106
	v_lshlrev_b32_e32 v91, 2, v82
	v_or_b32_e32 v82, s6, v130
	s_lshl_b32 s7, s75, 5
	v_mul_lo_u32 v92, v82, s2
	v_add_u32_e32 v82, 0x11a00, v83
	s_and_b32 s42, s7, 0xffffffc0
	s_or_b32 s7, s7, 32
	v_add_u32_e32 v94, s7, v82
	v_add_u32_e32 v99, s42, v83
	v_add_u32_e32 v83, s7, v83
	s_lshl_b32 s7, s82, 2
	s_lshl_b32 s41, s82, 5
	s_lshl_b32 s6, s81, 7
	s_add_i32 s7, s7, 0
	v_add_u32_e32 v132, 0, v71
	v_or_b32_e32 v71, s41, v130
	v_add_u32_e32 v133, 0, v108
	v_lshlrev_b32_e32 v73, 7, v126
	s_add_i32 s6, s7, s6
	v_and_b32_e32 v131, 63, v107
	v_lshlrev_b32_e32 v69, 10, v89
	v_sub_u32_e32 v73, v132, v73
	v_lshlrev_b32_e32 v85, 1, v89
	v_lshlrev_b32_e32 v66, 4, v66
	v_lshlrev_b32_e32 v68, 4, v68
	v_lshlrev_b32_e32 v70, 4, v70
	v_lshlrev_b32_e32 v72, 4, v72
	v_lshlrev_b32_e32 v84, 4, v84
	v_add_u32_e32 v67, 0, v67
	v_mul_u32_u24_e32 v136, 0x110, v71
	v_mul_u32_u24_e32 v71, 0x90, v71
	v_lshlrev_b32_e32 v89, 2, v109
	v_add_u32_e32 v93, s42, v82
	v_add_u32_e32 v95, 0x11a00, v133
	v_add_u32_e32 v96, 0x11a40, v133
	v_add_u32_e32 v97, 0x11a80, v133
	v_add_u32_e32 v98, 0x11ac0, v133
	s_lshl_b32 s92, s82, 7
	s_add_i32 s6, s6, 0x15e00
	v_mov_b32_e32 v82, 0
	s_mov_b32 s80, -2
	v_cmp_gt_u32_e32 vcc, 16, v131
	v_lshl_add_u64 v[128:129], v[86:87], 0, s[92:93]
	v_lshl_add_u32 v137, v130, 3, s6
	v_add_u32_e32 v138, v93, v136
	v_add_u32_e32 v139, v94, v136
	v_add_u32_e32 v140, v95, v136
	v_add_u32_e32 v141, v96, v136
	v_add_u32_e32 v142, v97, v136
	v_add_u32_e32 v143, v98, v136
	v_add_u32_e32 v144, v99, v136
	v_add_u32_e32 v145, v83, v136
	v_lshlrev_b32_e32 v146, 1, v69
	v_add_u32_e32 v147, 0, v66
	v_add_u32_e32 v148, 0, v68
	v_add_u32_e32 v149, 0, v70
	v_add_u32_e32 v150, 0, v72
	v_add_u32_e32 v151, 0, v88
	v_add_u32_e32 v152, 0, v84
	v_add_u32_e32 v153, v67, v85
	v_add_u32_e32 v154, v133, v71
	v_add_u32_e32 v155, v73, v108
	v_add_u32_e32 v156, 0, v89
	v_add_u32_e32 v157, v133, v90
	v_add_u32_e32 v158, 0, v91
	v_add_u32_e32 v159, v133, v92
	v_mov_b32_e32 v83, v82
	v_mov_b32_e32 v84, v82
	v_mov_b32_e32 v85, v82
	v_mov_b32_e32 v94, v82
	v_mov_b32_e32 v95, v82
	v_mov_b32_e32 v96, v82
	v_mov_b32_e32 v97, v82
	v_mov_b32_e32 v90, v82
	v_mov_b32_e32 v91, v82
	v_mov_b32_e32 v92, v82
	v_mov_b32_e32 v93, v82
	v_mov_b32_e32 v86, v82
	v_mov_b32_e32 v87, v82
	v_mov_b32_e32 v88, v82
	v_mov_b32_e32 v89, v82
	s_mov_b32 s81, 0x2c414000
	s_movk_i32 s82, 0x80
	s_branch .LBB0_1088

; #define LAS __attribute__((address_space(3)))
; __device__ __forceinline__ void rec_loop_task(const P& p, unsigned char* ws, int l, LAS unsigned char* lds, int tk) {
;     ...
;         const int st_rd = half ? R_ST1 : R_ST0, st_wr = half ? R_ST0 : R_ST1;
;         __syncthreads();
;         f32x4 emn[2];
;         if (half == 0) { REC_STAGE(pre); emn[0] = em1[0]; emn[1] = em1[1]; REC_FETCH(pre, em1, (ch + 2 < SEQ / 64 ? ch + 2 : SEQ / 64 - 1)); }
;         else { REC_STAGE(pre2); emn[0] = em2[0]; emn[1] = em2[1]; REC_FETCH(pre2, em2, (ch + 3 < SEQ / 64 ? ch + 3 : SEQ / 64 - 1)); }
;         __syncthreads();
;         f32x4 oacc[2] = {(f32x4){0.f, 0.f, 0.f, 0.f}, (f32x4){0.f, 0.f, 0.f, 0.f}};
;         __builtin_amdgcn_s_setprio(1);
; #pragma unroll
;         for (int kk = 0; kk < 4; ++kk) { const bf16x8_t qf = *(const LAS bf16x8_t*)(lds + R_QA + (ti * 16 + fr) * SQ + kk * 64 + fq * 16);
; #pragma unroll
;             for (int oj = 0; oj < 2; ++oj) { const bf16x8_t bb = *(const LAS bf16x8_t*)(lds + st_rd + ((2 * vi + oj) * 16 + fr) * SQ + kk * 64 + fq * 16); oacc[oj] = MFMA16(bb, qf, oacc[oj]); } }
;         bf16x8_t vf[2][2];
; #pragma unroll
;         for (int oj = 0; oj < 2; ++oj)
; #pragma unroll
;             for (int kk = 0; kk < 2; ++kk) vf[oj][kk] = *(const LAS bf16x8_t*)(lds + R_VT + ((2 * vi + oj) * 16 + fr) * SK + kk * 64 + fq * 16);
; #pragma unroll
;         for (int kk = 0; kk < 2; ++kk) { const bf16x8_t a = *(const LAS bf16x8_t*)(lds + R_PP + (ti * 16 + fr) * SK + kk * 64 + fq * 16);
; #pragma unroll
;             for (int oj = 0; oj < 2; ++oj) oacc[oj] = MFMA16(vf[oj][kk], a, oacc[oj]); }
; #pragma unroll
;         for (int cj = 0; cj < 2; ++cj) { const int ct = 2 * ti + cj;
;             const f32x4 dc = *(const LAS f32x4*)(lds + R_DEC + (ct * 16 + fq * 4) * 4);
; #pragma unroll
;             for (int oj = 0; oj < 2; ++oj) Sacc[cj][oj] = Sacc[cj][oj] * dc;
; #pragma unroll
;             for (int kk = 0; kk < 2; ++kk) { const bf16x8_t kf = *(const LAS bf16x8_t*)(lds + R_KBT + (ct * 16 + fr) * SK + kk * 64 + fq * 16);
; #pragma unroll
;                 for (int oj = 0; oj < 2; ++oj) Sacc[cj][oj] = MFMA16(kf, vf[oj][kk], Sacc[cj][oj]); } }
;         __builtin_amdgcn_s_setprio(0);
; #pragma unroll
;         for (int oj = 0; oj < 2; ++oj) *(f32x4*)(op + (size_t)((ch + half) * 64 + ti * 16 + fr) * D + (2 * vi + oj) * 16 + fq * 4) = oacc[oj];
.LBB0_1088:
	s_add_i32 s80, s80, 2
	s_min_u32 s6, s80, 29
	s_add_i32 s7, s6, 3
	s_add_i32 s6, s6, 2
	s_cmp_lt_u32 s80, 29
	s_cselect_b32 s7, s7, s6
	s_lshl_b32 s92, s7, 9
	v_lshl_or_b32 v172, s6, 17, v146
	s_mul_i32 s6, s6, 0xb200
	s_add_u32 s6, s38, s6
	s_addc_u32 s7, s39, 0
	s_waitcnt lgkmcnt(0)
	s_barrier
	v_lshl_add_u64 v[70:71], v[110:111], 0, s[92:93]
	v_lshl_add_u64 v[66:67], v[124:125], 0, v[172:173]
	s_waitcnt vmcnt(17)
	ds_write_b128 v147, v[2:5]
	s_waitcnt vmcnt(16)
	ds_write_b128 v148, v[6:9]
	s_waitcnt vmcnt(15)
	ds_write_b128 v149, v[10:13]
	s_waitcnt vmcnt(14)
	ds_write_b128 v150, v[14:17]
	s_waitcnt vmcnt(13)
	ds_write_b128 v151, v[18:21]
	s_waitcnt vmcnt(12)
	ds_write_b128 v152, v[22:25]
	s_waitcnt vmcnt(11)
	ds_write_b16 v153, v26 offset:45568
	ds_write_b16_d16_hi v153, v26 offset:45712
	ds_write_b16 v153, v27 offset:45856
	ds_write_b16_d16_hi v153, v27 offset:46000
	ds_write_b16 v153, v28 offset:46144
	ds_write_b16_d16_hi v153, v28 offset:46288
	ds_write_b16 v153, v29 offset:46432
	ds_write_b16_d16_hi v153, v29 offset:46576
	v_lshl_add_u64 v[2:3], s[6:7], 0, v[112:113]
	v_lshl_add_u64 v[6:7], s[6:7], 0, v[114:115]
	v_lshl_add_u64 v[10:11], s[6:7], 0, v[116:117]
	v_lshl_add_u64 v[14:15], s[6:7], 0, v[118:119]
	v_lshl_add_u64 v[18:19], s[6:7], 0, v[120:121]
	v_lshl_add_u64 v[22:23], s[6:7], 0, v[122:123]
	global_load_dwordx4 v[2:5], v[2:3], off
	s_nop 0
	global_load_dwordx4 v[6:9], v[6:7], off
	s_nop 0
	global_load_dwordx4 v[10:13], v[10:11], off
	s_nop 0
	global_load_dwordx4 v[14:17], v[14:15], off
	s_nop 0
	global_load_dwordx4 v[18:21], v[18:19], off
	s_nop 0
	global_load_dwordx4 v[22:25], v[22:23], off
	s_nop 0
	global_load_dwordx4 v[26:29], v[66:67], off
	s_nop 0
	global_load_dwordx4 v[66:69], v[70:71], off
	s_nop 0
	global_load_dwordx4 v[70:73], v[70:71], off offset:64
	s_waitcnt lgkmcnt(0)
	s_barrier
	s_setprio 1
	v_add_u32_e32 v127, v133, v136
	v_add_u32_e32 v160, v132, v108
	ds_read_b128 v[162:165], v160
	ds_read_b128 v[166:169], v127 offset:54784
	ds_read_b128 v[186:189], v127 offset:59136
	ds_read_b128 v[190:193], v160 offset:64
	ds_read_b128 v[194:197], v127 offset:54848
	ds_read_b128 v[198:201], v127 offset:59200
	ds_read_b128 v[202:205], v160 offset:128
	ds_read_b128 v[206:209], v127 offset:54912
	ds_read_b128 v[218:221], v127 offset:59264
	ds_read_b128 v[222:225], v160 offset:192
	ds_read_b128 v[226:229], v127 offset:54976
	ds_read_b128 v[230:233], v127 offset:59328
	ds_read_b128 v[234:237], v155 offset:17408
	ds_read_b128 v[238:241], v154 offset:45568
	ds_read_b128 v[242:245], v154 offset:47872
	s_waitcnt lgkmcnt(12)
	v_mfma_f32_16x16x32_bf16 v[102:105], v[166:169], v[162:165], 0
	v_mfma_f32_16x16x32_bf16 v[98:101], v[186:189], v[162:165], 0
	ds_read_b128 v[250:253], v155 offset:17472
	ds_read_b128 v[162:165], v154 offset:45632
	ds_read_b128 v[166:169], v154 offset:47936
	s_waitcnt lgkmcnt(12)
	v_mfma_f32_16x16x32_bf16 v[102:105], v[194:197], v[190:193], v[102:105]
	v_mfma_f32_16x16x32_bf16 v[98:101], v[198:201], v[190:193], v[98:101]
	ds_read_b128 v[186:189], v156 offset:45056
	ds_read_b128 v[190:193], v157 offset:26624
	ds_read_b128 v[194:197], v157 offset:26688
	s_waitcnt lgkmcnt(12)
	v_mfma_f32_16x16x32_bf16 v[102:105], v[206:209], v[202:205], v[102:105]
	v_mfma_f32_16x16x32_bf16 v[98:101], v[218:221], v[202:205], v[98:101]
	ds_read_b128 v[198:201], v158 offset:45056
	ds_read_b128 v[202:205], v159 offset:26624
	ds_read_b128 v[206:209], v159 offset:26688
	s_waitcnt lgkmcnt(12)
	v_mfma_f32_16x16x32_bf16 v[102:105], v[226:229], v[222:225], v[102:105]
	v_mfma_f32_16x16x32_bf16 v[98:101], v[230:233], v[222:225], v[98:101]
	s_waitcnt lgkmcnt(9)
	v_mfma_f32_16x16x32_bf16 v[102:105], v[238:241], v[234:237], v[102:105]
	v_mfma_f32_16x16x32_bf16 v[98:101], v[242:245], v[234:237], v[98:101]
	s_waitcnt lgkmcnt(6)
	v_mfma_f32_16x16x32_bf16 v[102:105], v[162:165], v[250:253], v[102:105]
	v_mfma_f32_16x16x32_bf16 v[98:101], v[166:169], v[250:253], v[98:101]
	s_waitcnt lgkmcnt(3)
	v_pk_mul_f32 v[82:83], v[82:83], v[186:187]
	v_pk_mul_f32 v[84:85], v[84:85], v[188:189]
	v_pk_mul_f32 v[94:95], v[94:95], v[186:187]
	v_pk_mul_f32 v[96:97], v[96:97], v[188:189]
	s_nop 1
	v_mfma_f32_16x16x32_bf16 v[82:85], v[190:193], v[238:241], v[82:85]
	v_mfma_f32_16x16x32_bf16 v[94:97], v[190:193], v[242:245], v[94:97]
	v_mfma_f32_16x16x32_bf16 v[82:85], v[194:197], v[162:165], v[82:85]
	v_mfma_f32_16x16x32_bf16 v[94:97], v[194:197], v[166:169], v[94:97]
	s_waitcnt lgkmcnt(0)
	v_pk_mul_f32 v[90:91], v[90:91], v[198:199]
	v_pk_mul_f32 v[92:93], v[92:93], v[200:201]
	v_pk_mul_f32 v[86:87], v[86:87], v[198:199]
	v_pk_mul_f32 v[88:89], v[88:89], v[200:201]
	s_nop 1
	v_mfma_f32_16x16x32_bf16 v[90:93], v[202:205], v[238:241], v[90:93]
	v_mfma_f32_16x16x32_bf16 v[86:89], v[202:205], v[242:245], v[86:89]
	v_mfma_f32_16x16x32_bf16 v[90:93], v[206:209], v[162:165], v[90:93]
	v_mfma_f32_16x16x32_bf16 v[86:89], v[206:209], v[166:169], v[86:89]
	s_setprio 0
	v_ashrrev_i32_e32 v127, 31, v126
	v_lshlrev_b64 v[162:163], 8, v[126:127]
	v_lshl_add_u64 v[162:163], v[128:129], 0, v[162:163]
	global_store_dwordx4 v[162:163], v[102:105], off
	global_store_dwordx4 v[162:163], v[98:101], off offset:64
	s_nop 1
	v_pk_mul_f32 v[100:101], v[100:101], v[100:101]
	v_pk_mul_f32 v[98:99], v[98:99], v[98:99]
	v_pk_fma_f32 v[100:101], v[104:105], v[104:105], v[100:101]
	v_pk_fma_f32 v[98:99], v[102:103], v[102:103], v[98:99]
	s_nop 0
	v_add_f32_e32 v98, v98, v99
	v_add_f32_e32 v99, v100, v101
	v_add_f32_e32 v98, v98, v99
	v_mov_b32_e32 v99, v98
	s_nop 1
	v_permlane16_swap_b32_e32 v98, v99
	s_nop 1
	v_add_f32_e32 v98, v98, v99
	v_mov_b32_e32 v99, v98
	s_nop 1
	v_permlane32_swap_b32_e32 v98, v99
	s_nop 1
	v_add_f32_e32 v98, v98, v99
	s_and_saveexec_b64 s[6:7], vcc
	s_cbranch_execz .LBB0_1090
	s_nop 0
	s_nop 0
	ds_write_b32 v137, v98
; #define LAS __attribute__((address_space(3)))
; __device__ __forceinline__ void rec_loop_task(const P& p, unsigned char* ws, int l, LAS unsigned char* lds, int tk) {
;     ...
;         const int st_rd = half ? R_ST1 : R_ST0, st_wr = half ? R_ST0 : R_ST1;
;         __syncthreads();
;         f32x4 emn[2];
;         if (half == 0) { REC_STAGE(pre); emn[0] = em1[0]; emn[1] = em1[1]; REC_FETCH(pre, em1, (ch + 2 < SEQ / 64 ? ch + 2 : SEQ / 64 - 1)); }
;         else { REC_STAGE(pre2); emn[0] = em2[0]; emn[1] = em2[1]; REC_FETCH(pre2, em2, (ch + 3 < SEQ / 64 ? ch + 3 : SEQ / 64 - 1)); }
;         __syncthreads();
;         f32x4 oacc[2] = {(f32x4){0.f, 0.f, 0.f, 0.f}, (f32x4){0.f, 0.f, 0.f, 0.f}};
;         __builtin_amdgcn_s_setprio(1);
; #pragma unroll
;         for (int kk = 0; kk < 4; ++kk) { const bf16x8_t qf = *(const LAS bf16x8_t*)(lds + R_QA + (ti * 16 + fr) * SQ + kk * 64 + fq * 16);
; #pragma unroll
;             for (int oj = 0; oj < 2; ++oj) { const bf16x8_t bb = *(const LAS bf16x8_t*)(lds + st_rd + ((2 * vi + oj) * 16 + fr) * SQ + kk * 64 + fq * 16); oacc[oj] = MFMA16(bb, qf, oacc[oj]); } }
;         bf16x8_t vf[2][2];
; #pragma unroll
;         for (int oj = 0; oj < 2; ++oj)
; #pragma unroll
;             for (int kk = 0; kk < 2; ++kk) vf[oj][kk] = *(const LAS bf16x8_t*)(lds + R_VT + ((2 * vi + oj) * 16 + fr) * SK + kk * 64 + fq * 16);
; #pragma unroll
;         for (int kk = 0; kk < 2; ++kk) { const bf16x8_t a = *(const LAS bf16x8_t*)(lds + R_PP + (ti * 16 + fr) * SK + kk * 64 + fq * 16);
; #pragma unroll
;             for (int oj = 0; oj < 2; ++oj) oacc[oj] = MFMA16(vf[oj][kk], a, oacc[oj]); }
; #pragma unroll
;         for (int cj = 0; cj < 2; ++cj) { const int ct = 2 * ti + cj;
;             const f32x4 dc = *(const LAS f32x4*)(lds + R_DEC + (ct * 16 + fq * 4) * 4);
; #pragma unroll
;             for (int oj = 0; oj < 2; ++oj) Sacc[cj][oj] = Sacc[cj][oj] * dc;
; #pragma unroll
;             for (int kk = 0; kk < 2; ++kk) { const bf16x8_t kf = *(const LAS bf16x8_t*)(lds + R_KBT + (ct * 16 + fr) * SK + kk * 64 + fq * 16);
; #pragma unroll
;                 for (int oj = 0; oj < 2; ++oj) Sacc[cj][oj] = MFMA16(kf, vf[oj][kk], Sacc[cj][oj]); } }
;         __builtin_amdgcn_s_setprio(0);
; #pragma unroll
;         for (int oj = 0; oj < 2; ++oj) *(f32x4*)(op + (size_t)((ch + half) * 64 + ti * 16 + fr) * D + (2 * vi + oj) * 16 + fq * 4) = oacc[oj];
.LBB0_1090:
	s_or_b64 exec, exec, s[6:7]
	s_min_u32 s42, s80, 28
	s_add_i32 s43, s42, 3
	s_mul_i32 s6, s43, 0xb200
	s_add_u32 s6, s38, s6
	s_addc_u32 s7, s39, 0
	s_add_i32 s42, s42, 4
	s_waitcnt vmcnt(21)
	v_pk_mul_f32 v[100:101], v[80:81], v[84:85]
	v_pk_mul_f32 v[104:105], v[78:79], v[82:83]
	v_pk_mul_f32 v[80:81], v[80:81], v[96:97]
	v_pk_mul_f32 v[78:79], v[78:79], v[94:95]
	s_cmp_lt_u32 s80, 28
	v_cvt_pk_bf16_f32 v78, v78, v79
	v_cvt_pk_bf16_f32 v79, v80, v81
	s_cselect_b32 s42, s42, s43
	ds_write_b64 v138, v[78:79] offset:4352
	s_waitcnt vmcnt(20)
	v_pk_mul_f32 v[78:79], v[76:77], v[92:93]
	v_pk_mul_f32 v[80:81], v[74:75], v[90:91]
	v_pk_mul_f32 v[76:77], v[76:77], v[88:89]
	v_pk_mul_f32 v[74:75], v[74:75], v[86:87]
	v_lshl_or_b32 v172, s43, 17, v146
	s_lshl_b32 s92, s42, 9
	v_cvt_pk_bf16_f32 v104, v104, v105
	v_cvt_pk_bf16_f32 v105, v100, v101
	v_cvt_pk_bf16_f32 v80, v80, v81
	v_cvt_pk_bf16_f32 v81, v78, v79
	v_cvt_pk_bf16_f32 v74, v74, v75
	v_cvt_pk_bf16_f32 v75, v76, v77
	s_waitcnt lgkmcnt(1)
	v_lshl_add_u64 v[98:99], v[124:125], 0, v[172:173]
	v_lshl_add_u64 v[102:103], v[110:111], 0, s[92:93]
	ds_write_b64 v138, v[104:105]
	ds_write_b64 v139, v[80:81]
	ds_write_b64 v139, v[74:75] offset:4352
	s_waitcnt lgkmcnt(0)
	s_barrier
	s_waitcnt vmcnt(19)
	ds_write_b128 v147, v[30:33]
	s_waitcnt vmcnt(18)
	ds_write_b128 v148, v[34:37]
	s_waitcnt vmcnt(17)
	ds_write_b128 v149, v[38:41]
	s_waitcnt vmcnt(16)
	ds_write_b128 v150, v[42:45]
	s_waitcnt vmcnt(15)
	ds_write_b128 v151, v[50:53]
	s_waitcnt vmcnt(14)
	ds_write_b128 v152, v[54:57]
	s_waitcnt vmcnt(13)
	ds_write_b16 v153, v46 offset:45568
	ds_write_b16_d16_hi v153, v46 offset:45712
	ds_write_b16 v153, v47 offset:45856
	ds_write_b16_d16_hi v153, v47 offset:46000
	ds_write_b16 v153, v48 offset:46144
	ds_write_b16_d16_hi v153, v48 offset:46288
	ds_write_b16 v153, v49 offset:46432
	ds_write_b16_d16_hi v153, v49 offset:46576
	v_lshl_add_u64 v[30:31], s[6:7], 0, v[112:113]
	v_lshl_add_u64 v[34:35], s[6:7], 0, v[114:115]
	v_lshl_add_u64 v[38:39], s[6:7], 0, v[116:117]
	v_lshl_add_u64 v[42:43], s[6:7], 0, v[118:119]
	v_lshl_add_u64 v[46:47], s[6:7], 0, v[120:121]
	v_lshl_add_u64 v[48:49], s[6:7], 0, v[122:123]
	global_load_dwordx4 v[30:33], v[30:31], off
	s_nop 0
	global_load_dwordx4 v[34:37], v[34:35], off
	s_nop 0
	global_load_dwordx4 v[38:41], v[38:39], off
	s_nop 0
	global_load_dwordx4 v[42:45], v[42:43], off
	s_nop 0
	global_load_dwordx4 v[50:53], v[46:47], off
	global_load_dwordx4 v[54:57], v[48:49], off
	s_nop 0
	global_load_dwordx4 v[46:49], v[98:99], off
	s_nop 0
	global_load_dwordx4 v[98:101], v[102:103], off
	s_nop 0
	global_load_dwordx4 v[102:105], v[102:103], off offset:64
	s_waitcnt lgkmcnt(0)
	s_barrier
	s_setprio 1
	ds_read_b128 v[162:165], v160
	ds_read_b128 v[166:169], v140
	ds_read_b128 v[186:189], v140 offset:4352
	ds_read_b128 v[190:193], v160 offset:64
	ds_read_b128 v[194:197], v141
	ds_read_b128 v[198:201], v141 offset:4352
	ds_read_b128 v[202:205], v160 offset:128
	ds_read_b128 v[206:209], v142
	ds_read_b128 v[218:221], v142 offset:4352
	ds_read_b128 v[222:225], v160 offset:192
	ds_read_b128 v[226:229], v143
	ds_read_b128 v[230:233], v143 offset:4352
	ds_read_b128 v[234:237], v155 offset:17408
	ds_read_b128 v[238:241], v154 offset:45568
	ds_read_b128 v[242:245], v154 offset:47872
	s_waitcnt lgkmcnt(12)
	v_mfma_f32_16x16x32_bf16 v[78:81], v[166:169], v[162:165], 0
	v_mfma_f32_16x16x32_bf16 v[74:77], v[186:189], v[162:165], 0
	ds_read_b128 v[250:253], v155 offset:17472
	ds_read_b128 v[162:165], v154 offset:45632
	ds_read_b128 v[166:169], v154 offset:47936
	s_waitcnt lgkmcnt(12)
	v_mfma_f32_16x16x32_bf16 v[78:81], v[194:197], v[190:193], v[78:81]
	v_mfma_f32_16x16x32_bf16 v[74:77], v[198:201], v[190:193], v[74:77]
	ds_read_b128 v[186:189], v156 offset:45056
	ds_read_b128 v[190:193], v157 offset:26624
	ds_read_b128 v[194:197], v157 offset:26688
	s_waitcnt lgkmcnt(12)
	v_mfma_f32_16x16x32_bf16 v[78:81], v[206:209], v[202:205], v[78:81]
	v_mfma_f32_16x16x32_bf16 v[74:77], v[218:221], v[202:205], v[74:77]
	ds_read_b128 v[198:201], v158 offset:45056
	ds_read_b128 v[202:205], v159 offset:26624
	ds_read_b128 v[206:209], v159 offset:26688
	s_waitcnt lgkmcnt(12)
	v_mfma_f32_16x16x32_bf16 v[78:81], v[226:229], v[222:225], v[78:81]
	v_mfma_f32_16x16x32_bf16 v[74:77], v[230:233], v[222:225], v[74:77]
	s_waitcnt lgkmcnt(9)
	v_mfma_f32_16x16x32_bf16 v[78:81], v[238:241], v[234:237], v[78:81]
	v_mfma_f32_16x16x32_bf16 v[74:77], v[242:245], v[234:237], v[74:77]
	s_waitcnt lgkmcnt(6)
	v_mfma_f32_16x16x32_bf16 v[78:81], v[162:165], v[250:253], v[78:81]
	v_mfma_f32_16x16x32_bf16 v[74:77], v[166:169], v[250:253], v[74:77]
	s_waitcnt lgkmcnt(3)
	v_pk_mul_f32 v[82:83], v[82:83], v[186:187]
	v_pk_mul_f32 v[84:85], v[84:85], v[188:189]
	v_pk_mul_f32 v[94:95], v[94:95], v[186:187]
	v_pk_mul_f32 v[96:97], v[96:97], v[188:189]
	s_nop 1
	v_mfma_f32_16x16x32_bf16 v[82:85], v[190:193], v[238:241], v[82:85]
	v_mfma_f32_16x16x32_bf16 v[94:97], v[190:193], v[242:245], v[94:97]
	v_mfma_f32_16x16x32_bf16 v[82:85], v[194:197], v[162:165], v[82:85]
	v_mfma_f32_16x16x32_bf16 v[94:97], v[194:197], v[166:169], v[94:97]
	s_waitcnt lgkmcnt(0)
	v_pk_mul_f32 v[90:91], v[90:91], v[198:199]
	v_pk_mul_f32 v[92:93], v[92:93], v[200:201]
	v_pk_mul_f32 v[86:87], v[86:87], v[198:199]
	v_pk_mul_f32 v[88:89], v[88:89], v[200:201]
	s_nop 1
	v_mfma_f32_16x16x32_bf16 v[90:93], v[202:205], v[238:241], v[90:93]
	v_mfma_f32_16x16x32_bf16 v[86:89], v[202:205], v[242:245], v[86:89]
	v_mfma_f32_16x16x32_bf16 v[90:93], v[206:209], v[162:165], v[90:93]
	v_mfma_f32_16x16x32_bf16 v[86:89], v[206:209], v[166:169], v[86:89]
	s_setprio 0
	v_add_u32_e32 v160, 64, v126
	v_ashrrev_i32_e32 v161, 31, v160
	v_lshlrev_b64 v[160:161], 8, v[160:161]
	v_lshl_add_u64 v[160:161], v[128:129], 0, v[160:161]
	global_store_dwordx4 v[160:161], v[78:81], off
	global_store_dwordx4 v[160:161], v[74:77], off offset:64
	s_nop 1
	v_pk_mul_f32 v[76:77], v[76:77], v[76:77]
	v_pk_mul_f32 v[74:75], v[74:75], v[74:75]
	v_pk_fma_f32 v[76:77], v[80:81], v[80:81], v[76:77]
	v_pk_fma_f32 v[74:75], v[78:79], v[78:79], v[74:75]
	s_nop 0
	v_add_f32_e32 v74, v74, v75
	v_add_f32_e32 v75, v76, v77
	v_add_f32_e32 v74, v74, v75
	v_mov_b32_e32 v75, v74
	s_nop 1
	v_permlane16_swap_b32_e32 v74, v75
	s_nop 1
	v_add_f32_e32 v74, v74, v75
	v_mov_b32_e32 v75, v74
	s_nop 1
	v_permlane32_swap_b32_e32 v74, v75
	s_nop 1
	v_add_f32_e32 v74, v74, v75
	s_and_saveexec_b64 s[6:7], vcc
	s_cbranch_execz .LBB0_1087
	s_nop 0
	s_nop 0
	ds_write_b32 v137, v74 offset:512
	s_branch .LBB0_1087

; #define LAS __attribute__((address_space(3)))
; __device__ __forceinline__ unsigned pk2(float lo, float hi) { return pg8::cvt_pk_bf16(lo, hi); }
; __device__ __forceinline__ void rec_loop_task(const P& p, unsigned char* ws, int l, LAS unsigned char* lds, int tk) {
;     ...
;     { f32x4 qa, qb, qc, qd; const float* x0 = xo + tid * 4;
;       ld_sc1_4x4(x0, x0 + SEQ, x0 + 2 * SEQ, x0 + 3 * SEQ, qa, qb, qc, qd);
;       float s4[4];
; #pragma unroll
;       for (int j = 0; j < 4; ++j) s4[j] = (qa[j] + qb[j]) + (nsl > 2 ? qc[j] + qd[j] : 0.f);
;       const float iv = gla ? (1.f / GV) : (1.f / HV);
;       *(LAS f32x4*)(lds + R_ORS + tid * 16) = (f32x4){rsqrtf(s4[0] * iv + EPS), rsqrtf(s4[1] * iv + EPS), rsqrtf(s4[2] * iv + EPS), rsqrtf(s4[3] * iv + EPS)}; }
;     __syncthreads();
;     { const int c4 = (tid & 15) * 4, r0 = tid >> 4;
;       const f32x4 gn4 = *(const f32x4*)((gla ? p.gln + l * GV : p.hgn + l * HV) + vs * 64 + c4);
;       const bf16_t* gate = (const bf16_t*)(ws + (gla ? WS_RG : WS_GHG)) + (size_t)(b * SEQ) * 1024 + head * V + vs * 64 + c4;
;       bf16_t* og = (bf16_t*)(ws + WS_OG) + (size_t)(b * SEQ) * D + (gla ? 1024 : 0) + head * V + vs * 64 + c4;
;       const float* orow = op + c4;
; #pragma nounroll
;       for (int rb = 0; rb < SEQ; rb += 256) {
;           f32x4 ov[8]; u32x2 gw[8];
; #pragma unroll
;           for (int i = 0; i < 8; ++i) { const int r = rb + i * 32 + r0; ov[i] = *(const f32x4*)(orow + (size_t)r * D); gw[i] = *(const u32x2*)(gate + (size_t)r * 1024); }
; #pragma unroll
;           for (int i = 0; i < 8; ++i) { const int r = rb + i * 32 + r0; const float rs = ((const LAS float*)(lds + R_ORS))[r];
;               const float g0 = __uint_as_float(gw[i].x << 16), g1 = __uint_as_float(gw[i].x & 0xffff0000u), g2 = __uint_as_float(gw[i].y << 16), g3 = __uint_as_float(gw[i].y & 0xffff0000u);
;               u32x2 wv; wv.x = pk2(ov[i][0] * rs * gn4[0] * g0, ov[i][1] * rs * gn4[1] * g1); wv.y = pk2(ov[i][2] * rs * gn4[2] * g2, ov[i][3] * rs * gn4[3] * g3);
;               *(u32x2*)(og + (size_t)r * D) = wv; } } }
.LBB0_1111:
	v_lshl_add_u64 v[20:21], v[2:3], 2, s[34:35]
	s_mov_b64 s[0:1], 0x4000
	v_lshl_add_u64 v[24:25], v[20:21], 0, s[0:1]
	s_mov_b64 s[0:1], 0x6000
	s_barrier
	v_lshl_add_u64 v[22:23], v[20:21], 0, s[96:97]
	v_lshl_add_u64 v[26:27], v[20:21], 0, s[0:1]
	global_load_dwordx4 v[4:7], v[20:21], off sc1
	global_load_dwordx4 v[8:11], v[22:23], off sc1
	global_load_dwordx4 v[12:15], v[24:25], off sc1
	global_load_dwordx4 v[16:19], v[26:27], off sc1
	s_waitcnt vmcnt(0)
	s_and_b64 s[0:1], s[36:37], exec
	v_add_f32_e32 v3, v4, v8
	v_add_f32_e32 v4, v12, v16
	v_cndmask_b32_e64 v4, 0, v4, s[36:37]
	v_add_f32_e32 v3, v3, v4
	v_add_f32_e32 v4, v5, v9
	v_add_f32_e32 v5, v13, v17
	v_cndmask_b32_e64 v5, 0, v5, s[36:37]
	v_add_f32_e32 v5, v4, v5
	v_add_f32_e32 v4, v6, v10
	v_add_f32_e32 v6, v14, v18
	v_cndmask_b32_e64 v6, 0, v6, s[36:37]
	v_add_f32_e32 v6, v4, v6
	v_add_f32_e32 v4, v7, v11
	v_add_f32_e32 v7, v15, v19
	v_cndmask_b32_e64 v8, v216, v217, s[36:37]
	v_cndmask_b32_e64 v7, 0, v7, s[36:37]
	v_fmaak_f32 v3, v8, v3, 0x358637bd
	v_add_f32_e32 v7, v4, v7
	v_cmp_gt_f32_e32 vcc, s5, v3
	v_mul_f32_e32 v4, 0x4b800000, v3
	s_cselect_b32 s0, 8, 7
	v_cndmask_b32_e32 v3, v3, v4, vcc
	v_rsq_f32_e32 v3, v3
	s_mov_b32 s1, 0x30614000
	s_cselect_b32 s6, s1, 0x2b394000
	s_cselect_b32 s7, s91, s58
	v_mul_f32_e32 v4, 0x45800000, v3
	v_cndmask_b32_e32 v4, v3, v4, vcc
	v_fmaak_f32 v3, v8, v5, 0x358637bd
	v_cmp_gt_f32_e32 vcc, s5, v3
	v_mul_f32_e32 v5, 0x4b800000, v3
	s_cselect_b32 s34, s95, s59
	v_cndmask_b32_e32 v3, v3, v5, vcc
	v_rsq_f32_e32 v3, v3
	s_lshl_b32 s0, s14, s0
	s_ashr_i32 s1, s0, 31
	s_lshl_b64 s[0:1], s[0:1], 2
	v_mul_f32_e32 v5, 0x45800000, v3
	v_cndmask_b32_e32 v5, v3, v5, vcc
	v_fmaak_f32 v3, v8, v6, 0x358637bd
	v_cmp_gt_f32_e32 vcc, s5, v3
	v_mul_f32_e32 v6, 0x4b800000, v3
	s_add_u32 s0, s34, s0
	v_cndmask_b32_e32 v3, v3, v6, vcc
	v_rsq_f32_e32 v3, v3
	s_addc_u32 s1, s7, s1
	v_readlane_b32 s2, v248, 16
	v_and_b32_e32 v2, 60, v2
	v_mul_f32_e32 v6, 0x45800000, v3
	v_cndmask_b32_e32 v6, v3, v6, vcc
	v_fmaak_f32 v3, v8, v7, 0x358637bd
	v_cmp_gt_f32_e32 vcc, s5, v3
	v_mul_f32_e32 v7, 0x4b800000, v3
	s_add_u32 s0, s0, s78
	v_cndmask_b32_e32 v3, v3, v7, vcc
	v_rsq_f32_e32 v3, v3
	s_addc_u32 s1, s1, 0
	v_lshlrev_b32_e32 v2, 2, v2
	v_lshlrev_b32_e32 v172, 3, v130
	v_mul_f32_e32 v7, 0x45800000, v3
	v_cndmask_b32_e32 v7, v3, v7, vcc
	v_lshl_add_u32 v3, v107, 4, s2
	ds_write_b128 v3, v[4:7]
	s_waitcnt lgkmcnt(0)
	s_barrier
	global_load_dwordx4 v[2:5], v2, s[0:1]
	v_ashrrev_i32_e32 v6, 4, v107
	v_ashrrev_i32_e32 v7, 31, v6
	v_lshlrev_b64 v[8:9], 12, v[6:7]
	s_lshl_b64 s[0:1], s[28:29], 12
	v_lshl_add_u64 v[8:9], v[8:9], 0, s[0:1]
	s_lshl_b32 s0, s20, 1
	s_add_u32 s0, s30, s0
	v_or3_b32 v8, v8, s74, v172
	s_addc_u32 s1, s31, 0
	v_lshl_add_u64 v[38:39], s[0:1], 0, v[8:9]
	s_add_u32 s0, s74, s26
	s_addc_u32 s1, 0, s27
	s_add_u32 s0, s0, s6
	v_lshlrev_b64 v[8:9], 11, v[6:7]
	s_addc_u32 s1, s1, 0
	v_lshl_add_u64 v[8:9], s[0:1], 0, v[8:9]
	v_lshl_add_u32 v60, v6, 2, s2
	v_lshl_add_u64 v[8:9], v[8:9], 0, v[172:173]
	v_lshlrev_b64 v[6:7], 8, v[6:7]
	v_lshl_add_u64 v[40:41], v[8:9], 0, s[30:31]
	v_lshl_add_u64 v[6:7], v[6:7], 0, s[22:23]
	v_lshlrev_b32_e32 v8, 4, v130
	s_add_u32 s0, s24, s21
	s_add_u32 s0, s0, s73
	s_lshl_b32 s0, s0, 11
	v_or_b32_e32 v6, v6, v8
	s_mov_b32 s1, 0
	v_lshl_add_u64 v[42:43], s[0:1], 0, v[6:7]
	s_movk_i32 s0, 0xff00
.LBB0_1112:
	v_lshl_add_u64 v[6:7], s[12:13], 0, v[42:43]
	v_add_co_u32_e32 v8, vcc, 0x36914000, v6
	v_lshl_add_u64 v[44:45], s[12:13], 0, v[40:41]
	s_nop 0
	v_addc_co_u32_e32 v9, vcc, 0, v7, vcc
	global_load_dwordx4 v[34:37], v[8:9], off
	global_load_dwordx2 v[58:59], v[44:45], off
	v_add_co_u32_e32 v8, vcc, 0x36916000, v6
	s_mov_b32 s1, 0x10000
	s_nop 0
	v_addc_co_u32_e32 v9, vcc, 0, v7, vcc
	global_load_dwordx4 v[30:33], v[8:9], off
	v_add_co_u32_e32 v8, vcc, s1, v44
	ds_read2_b32 v[62:63], v60 offset1:32
	s_nop 0
	v_addc_co_u32_e32 v9, vcc, 0, v45, vcc
	global_load_dwordx2 v[56:57], v[8:9], off
	v_add_co_u32_e32 v8, vcc, 0x36918000, v6
	s_mov_b32 s1, 0x3ab14000
	s_nop 0
	v_addc_co_u32_e32 v9, vcc, 0, v7, vcc
	global_load_dwordx4 v[26:29], v[8:9], off
	v_add_co_u32_e32 v8, vcc, s83, v44
	s_mov_b64 s[6:7], 0x100000
	s_nop 0
	v_addc_co_u32_e32 v9, vcc, 0, v45, vcc
	global_load_dwordx2 v[54:55], v[8:9], off
	v_add_co_u32_e32 v8, vcc, 0x3691a000, v6
	s_addk_i32 s0, 0x100
	s_nop 0
	v_addc_co_u32_e32 v9, vcc, 0, v7, vcc
	global_load_dwordx4 v[22:25], v[8:9], off
	v_add_co_u32_e32 v8, vcc, 0x30000, v44
	v_lshl_add_u64 v[40:41], v[40:41], 0, s[64:65]
	s_nop 0
	v_addc_co_u32_e32 v9, vcc, 0, v45, vcc
	global_load_dwordx2 v[52:53], v[8:9], off
	v_add_co_u32_e32 v8, vcc, 0x3691c000, v6
	s_cmpk_lt_u32 s0, 0x700
	s_nop 0
	v_addc_co_u32_e32 v9, vcc, 0, v7, vcc
	global_load_dwordx4 v[18:21], v[8:9], off
	v_add_co_u32_e32 v8, vcc, 0x40000, v44
	s_waitcnt vmcnt(8) lgkmcnt(0)
	v_pk_mul_f32 v[34:35], v[34:35], v[62:63] op_sel_hi:[1,0]
	v_addc_co_u32_e32 v9, vcc, 0, v45, vcc
	global_load_dwordx2 v[50:51], v[8:9], off
	v_add_co_u32_e32 v8, vcc, 0x3691e000, v6
	v_pk_mul_f32 v[34:35], v[2:3], v[34:35]
	s_nop 0
	v_addc_co_u32_e32 v9, vcc, 0, v7, vcc
	global_load_dwordx4 v[14:17], v[8:9], off
	v_add_co_u32_e32 v8, vcc, 0x50000, v44
	v_pk_mul_f32 v[36:37], v[36:37], v[62:63] op_sel_hi:[1,0]
	s_nop 0
	v_addc_co_u32_e32 v9, vcc, 0, v45, vcc
	global_load_dwordx2 v[48:49], v[8:9], off
	v_add_co_u32_e32 v8, vcc, 0x36920000, v6
	v_pk_mul_f32 v[36:37], v[4:5], v[36:37]
	s_nop 0
	v_addc_co_u32_e32 v9, vcc, 0, v7, vcc
	global_load_dwordx4 v[10:13], v[8:9], off
	v_add_co_u32_e32 v8, vcc, 0x60000, v44
	s_nop 1
	v_addc_co_u32_e32 v9, vcc, 0, v45, vcc
	global_load_dwordx2 v[46:47], v[8:9], off
	v_add_co_u32_e32 v6, vcc, 0x36922000, v6
	s_nop 1
	v_addc_co_u32_e32 v7, vcc, 0, v7, vcc
	global_load_dwordx4 v[6:9], v[6:7], off
	v_add_co_u32_e32 v44, vcc, 0x70000, v44
	s_waitcnt vmcnt(13)
; #define LAS __attribute__((address_space(3)))
; __device__ __forceinline__ unsigned pk2(float lo, float hi) { return pg8::cvt_pk_bf16(lo, hi); }
; __device__ __forceinline__ void rec_loop_task(const P& p, unsigned char* ws, int l, LAS unsigned char* lds, int tk) {
;     ...
;       for (int rb = 0; rb < SEQ; rb += 256) {
;           f32x4 ov[8]; u32x2 gw[8];
; #pragma unroll
;           for (int i = 0; i < 8; ++i) { const int r = rb + i * 32 + r0; ov[i] = *(const f32x4*)(orow + (size_t)r * D); gw[i] = *(const u32x2*)(gate + (size_t)r * 1024); }
; #pragma unroll
;           for (int i = 0; i < 8; ++i) { const int r = rb + i * 32 + r0; const float rs = ((const LAS float*)(lds + R_ORS))[r];
;               const float g0 = __uint_as_float(gw[i].x << 16), g1 = __uint_as_float(gw[i].x & 0xffff0000u), g2 = __uint_as_float(gw[i].y << 16), g3 = __uint_as_float(gw[i].y & 0xffff0000u);
;               u32x2 wv; wv.x = pk2(ov[i][0] * rs * gn4[0] * g0, ov[i][1] * rs * gn4[1] * g1); wv.y = pk2(ov[i][2] * rs * gn4[2] * g2, ov[i][3] * rs * gn4[3] * g3);
;               *(u32x2*)(og + (size_t)r * D) = wv; } } }
;     __syncthreads();
	v_lshlrev_b32_e32 v64, 16, v58
	v_addc_co_u32_e32 v45, vcc, 0, v45, vcc
	global_load_dwordx2 v[44:45], v[44:45], off
	v_and_b32_e32 v65, 0xffff0000, v58
	v_pk_mul_f32 v[34:35], v[34:35], v[64:65]
	s_nop 0
	v_cvt_pk_bf16_f32 v58, v34, v35
	v_lshlrev_b32_e32 v34, 16, v59
	v_and_b32_e32 v35, 0xffff0000, v59
	v_pk_mul_f32 v[34:35], v[36:37], v[34:35]
	s_nop 0
	v_cvt_pk_bf16_f32 v59, v34, v35
	v_lshl_add_u64 v[34:35], s[12:13], 0, v[38:39]
	v_add_co_u32_e32 v36, vcc, s1, v34
	s_mov_b32 s1, 0x3ab34000
	s_nop 0
	v_addc_co_u32_e32 v37, vcc, 0, v35, vcc
	global_store_dwordx2 v[36:37], v[58:59], off
	s_waitcnt vmcnt(13)
	v_lshlrev_b32_e32 v36, 16, v56
	v_and_b32_e32 v37, 0xffff0000, v56
	v_mov_b32_e32 v56, v63
	v_pk_mul_f32 v[30:31], v[30:31], v[56:57] op_sel_hi:[1,0]
	v_pk_mul_f32 v[32:33], v[32:33], v[56:57] op_sel_hi:[1,0]
	v_pk_mul_f32 v[30:31], v[2:3], v[30:31]
	v_pk_mul_f32 v[32:33], v[4:5], v[32:33]
	v_pk_mul_f32 v[30:31], v[30:31], v[36:37]
	v_lshlrev_b32_e32 v36, 16, v57
	v_and_b32_e32 v37, 0xffff0000, v57
	v_pk_mul_f32 v[32:33], v[32:33], v[36:37]
	v_cvt_pk_bf16_f32 v30, v30, v31
	v_cvt_pk_bf16_f32 v31, v32, v33
	v_add_co_u32_e32 v32, vcc, s1, v34
	s_mov_b32 s1, 0x3ab54000
	s_nop 0
	v_addc_co_u32_e32 v33, vcc, 0, v35, vcc
	global_store_dwordx2 v[32:33], v[30:31], off
	ds_read2_b32 v[30:31], v60 offset0:64 offset1:96
	s_waitcnt vmcnt(12)
	v_lshlrev_b32_e32 v32, 16, v54
	v_and_b32_e32 v33, 0xffff0000, v54
	v_lshl_add_u64 v[38:39], v[38:39], 0, s[6:7]
	s_mov_b64 s[6:7], 0x10000
	s_waitcnt lgkmcnt(0)
	v_pk_mul_f32 v[26:27], v[26:27], v[30:31] op_sel_hi:[1,0]
	v_pk_mul_f32 v[28:29], v[28:29], v[30:31] op_sel_hi:[1,0]
	v_pk_mul_f32 v[26:27], v[2:3], v[26:27]
	v_pk_mul_f32 v[28:29], v[4:5], v[28:29]
	v_pk_mul_f32 v[26:27], v[26:27], v[32:33]
	v_lshlrev_b32_e32 v32, 16, v55
	v_and_b32_e32 v33, 0xffff0000, v55
	v_pk_mul_f32 v[28:29], v[28:29], v[32:33]
	v_cvt_pk_bf16_f32 v26, v26, v27
	v_cvt_pk_bf16_f32 v27, v28, v29
	v_add_co_u32_e32 v28, vcc, s1, v34
	s_mov_b32 s1, 0x3ab74000
	s_nop 0
	v_addc_co_u32_e32 v29, vcc, 0, v35, vcc
	global_store_dwordx2 v[28:29], v[26:27], off
	v_mov_b32_e32 v28, v31
	s_waitcnt vmcnt(12)
	v_pk_mul_f32 v[22:23], v[22:23], v[28:29] op_sel_hi:[1,0]
	s_waitcnt vmcnt(11)
	v_lshlrev_b32_e32 v26, 16, v52
	v_and_b32_e32 v27, 0xffff0000, v52
	v_pk_mul_f32 v[22:23], v[2:3], v[22:23]
	v_pk_mul_f32 v[24:25], v[24:25], v[28:29] op_sel_hi:[1,0]
	v_pk_mul_f32 v[22:23], v[22:23], v[26:27]
	v_lshlrev_b32_e32 v26, 16, v53
	v_and_b32_e32 v27, 0xffff0000, v53
	v_pk_mul_f32 v[24:25], v[4:5], v[24:25]
	v_cvt_pk_bf16_f32 v22, v22, v23
	v_pk_mul_f32 v[24:25], v[24:25], v[26:27]
	v_lshl_add_u64 v[42:43], v[42:43], 0, s[6:7]
	v_cvt_pk_bf16_f32 v23, v24, v25
	v_add_co_u32_e32 v24, vcc, s1, v34
	s_mov_b32 s1, 0x3ab94000
	s_nop 0
	v_addc_co_u32_e32 v25, vcc, 0, v35, vcc
	global_store_dwordx2 v[24:25], v[22:23], off
	ds_read2_b32 v[22:23], v60 offset0:128 offset1:160
	s_waitcnt vmcnt(10)
	v_lshlrev_b32_e32 v24, 16, v50
	v_and_b32_e32 v25, 0xffff0000, v50
	s_waitcnt lgkmcnt(0)
	v_pk_mul_f32 v[18:19], v[18:19], v[22:23] op_sel_hi:[1,0]
	s_nop 0
	v_pk_mul_f32 v[18:19], v[2:3], v[18:19]
	v_pk_mul_f32 v[20:21], v[20:21], v[22:23] op_sel_hi:[1,0]
	v_pk_mul_f32 v[18:19], v[18:19], v[24:25]
	v_lshlrev_b32_e32 v24, 16, v51
	v_and_b32_e32 v25, 0xffff0000, v51
	v_pk_mul_f32 v[20:21], v[4:5], v[20:21]
	v_cvt_pk_bf16_f32 v18, v18, v19
	v_pk_mul_f32 v[20:21], v[20:21], v[24:25]
	s_nop 0
	v_cvt_pk_bf16_f32 v19, v20, v21
	v_add_co_u32_e32 v20, vcc, s1, v34
	s_mov_b32 s1, 0x3abb4000
	s_nop 0
	v_addc_co_u32_e32 v21, vcc, 0, v35, vcc
	global_store_dwordx2 v[20:21], v[18:19], off
	v_mov_b32_e32 v20, v23
	s_waitcnt vmcnt(10)
	v_pk_mul_f32 v[14:15], v[14:15], v[20:21] op_sel_hi:[1,0]
	s_waitcnt vmcnt(9)
	v_lshlrev_b32_e32 v18, 16, v48
	v_and_b32_e32 v19, 0xffff0000, v48
	v_pk_mul_f32 v[14:15], v[2:3], v[14:15]
	v_pk_mul_f32 v[16:17], v[16:17], v[20:21] op_sel_hi:[1,0]
	v_pk_mul_f32 v[14:15], v[14:15], v[18:19]
	v_lshlrev_b32_e32 v18, 16, v49
	v_and_b32_e32 v19, 0xffff0000, v49
	v_pk_mul_f32 v[16:17], v[4:5], v[16:17]
	v_cvt_pk_bf16_f32 v14, v14, v15
	v_pk_mul_f32 v[16:17], v[16:17], v[18:19]
	s_nop 0
	v_cvt_pk_bf16_f32 v15, v16, v17
	v_add_co_u32_e32 v16, vcc, s1, v34
	s_mov_b32 s1, 0x3abd4000
	s_nop 0
	v_addc_co_u32_e32 v17, vcc, 0, v35, vcc
	global_store_dwordx2 v[16:17], v[14:15], off
	ds_read2_b32 v[14:15], v60 offset0:192 offset1:224
	s_waitcnt vmcnt(8)
	v_lshlrev_b32_e32 v16, 16, v46
	v_and_b32_e32 v17, 0xffff0000, v46
	v_add_u32_e32 v60, 0x400, v60
	s_waitcnt lgkmcnt(0)
	v_pk_mul_f32 v[10:11], v[10:11], v[14:15] op_sel_hi:[1,0]
	s_nop 0
	v_pk_mul_f32 v[10:11], v[2:3], v[10:11]
	v_pk_mul_f32 v[12:13], v[12:13], v[14:15] op_sel_hi:[1,0]
	v_pk_mul_f32 v[10:11], v[10:11], v[16:17]
	v_lshlrev_b32_e32 v16, 16, v47
	v_and_b32_e32 v17, 0xffff0000, v47
	v_pk_mul_f32 v[12:13], v[4:5], v[12:13]
	v_cvt_pk_bf16_f32 v10, v10, v11
	v_pk_mul_f32 v[12:13], v[12:13], v[16:17]
	s_nop 0
	v_cvt_pk_bf16_f32 v11, v12, v13
	v_add_co_u32_e32 v12, vcc, s1, v34
	s_nop 1
	v_addc_co_u32_e32 v13, vcc, 0, v35, vcc
	global_store_dwordx2 v[12:13], v[10:11], off
	v_mov_b32_e32 v12, v15
	s_waitcnt vmcnt(8)
	v_pk_mul_f32 v[6:7], v[6:7], v[12:13] op_sel_hi:[1,0]
	s_waitcnt vmcnt(7)
	v_lshlrev_b32_e32 v10, 16, v44
	v_and_b32_e32 v11, 0xffff0000, v44
	v_pk_mul_f32 v[6:7], v[2:3], v[6:7]
	v_pk_mul_f32 v[8:9], v[8:9], v[12:13] op_sel_hi:[1,0]
	v_pk_mul_f32 v[6:7], v[6:7], v[10:11]
	v_lshlrev_b32_e32 v10, 16, v45
	v_and_b32_e32 v11, 0xffff0000, v45
	v_pk_mul_f32 v[8:9], v[4:5], v[8:9]
	v_cvt_pk_bf16_f32 v6, v6, v7
	v_pk_mul_f32 v[8:9], v[8:9], v[10:11]
	s_nop 0
	v_cvt_pk_bf16_f32 v7, v8, v9
	v_add_co_u32_e32 v8, vcc, 0x3abf4000, v34
	s_nop 1
	v_addc_co_u32_e32 v9, vcc, 0, v35, vcc
	global_store_dwordx2 v[8:9], v[6:7], off
	s_cbranch_scc1 .LBB0_1112
	s_add_i32 s45, s45, s57
	s_cmpk_gt_i32 s45, 0x7f
	s_barrier
	s_cbranch_scc0 .LBB0_1078

; __global__ void __launch_bounds__(NTHR, 2) mega(const Args a) {
	.amdhsa_kernel _Z4mega4Args
		.amdhsa_group_segment_fixed_size 0
		.amdhsa_private_segment_fixed_size 0
		.amdhsa_kernarg_size 464
		.amdhsa_user_sgpr_count 2
		.amdhsa_user_sgpr_dispatch_ptr 0
		.amdhsa_user_sgpr_queue_ptr 0
		.amdhsa_user_sgpr_kernarg_segment_ptr 1
		.amdhsa_user_sgpr_dispatch_id 0
		.amdhsa_user_sgpr_kernarg_preload_length 0
		.amdhsa_user_sgpr_kernarg_preload_offset 0
		.amdhsa_user_sgpr_private_segment_size 0
		.amdhsa_uses_dynamic_stack 0
		.amdhsa_enable_private_segment 0
		.amdhsa_system_sgpr_workgroup_id_x 1
		.amdhsa_system_sgpr_workgroup_id_y 0
		.amdhsa_system_sgpr_workgroup_id_z 0
		.amdhsa_system_sgpr_workgroup_info 0
		.amdhsa_system_vgpr_workitem_id 0
		.amdhsa_next_free_vgpr 256
		.amdhsa_next_free_sgpr 100
		.amdhsa_accum_offset 256
		.amdhsa_reserve_vcc 1
		.amdhsa_float_round_mode_32 0
		.amdhsa_float_round_mode_16_64 0
		.amdhsa_float_denorm_mode_32 3
		.amdhsa_float_denorm_mode_16_64 3
		.amdhsa_dx10_clamp 1
		.amdhsa_ieee_mode 1
		.amdhsa_fp16_overflow 0
		.amdhsa_tg_split 0
		.amdhsa_exception_fp_ieee_invalid_op 0
		.amdhsa_exception_fp_denorm_src 0
		.amdhsa_exception_fp_ieee_div_zero 0
		.amdhsa_exception_fp_ieee_overflow 0
		.amdhsa_exception_fp_ieee_underflow 0
		.amdhsa_exception_fp_ieee_inexact 0
		.amdhsa_exception_int_div_zero 0
	.end_amdhsa_kernel

; __global__ void __launch_bounds__(NTHR, 2) mega(const Args a) {
amdhsa.kernels:
  - .agpr_count:     0
    .args:
      - .offset:         0
        .size:           208
        .value_kind:     by_value
      - .offset:         208
        .size:           4
        .value_kind:     hidden_block_count_x
      - .offset:         212
        .size:           4
        .value_kind:     hidden_block_count_y
      - .offset:         216
        .size:           4
        .value_kind:     hidden_block_count_z
      - .offset:         220
        .size:           2
        .value_kind:     hidden_group_size_x
      - .offset:         222
        .size:           2
        .value_kind:     hidden_group_size_y
      - .offset:         224
        .size:           2
        .value_kind:     hidden_group_size_z
      - .offset:         226
        .size:           2
        .value_kind:     hidden_remainder_x
      - .offset:         228
        .size:           2
        .value_kind:     hidden_remainder_y
      - .offset:         230
        .size:           2
        .value_kind:     hidden_remainder_z
      - .offset:         248
        .size:           8
        .value_kind:     hidden_global_offset_x
      - .offset:         256
        .size:           8
        .value_kind:     hidden_global_offset_y
      - .offset:         264
        .size:           8
        .value_kind:     hidden_global_offset_z
      - .offset:         272
        .size:           2
        .value_kind:     hidden_grid_dims
      - .offset:         328
        .size:           4
        .value_kind:     hidden_dynamic_lds_size
    .group_segment_fixed_size: 0
    .kernarg_segment_align: 8
    .kernarg_segment_size: 464
    .language:       OpenCL C
    .language_version:
      - 2
      - 0
    .max_flat_workgroup_size: 512
    .name:           _Z4mega4Args
    .private_segment_fixed_size: 0
    .sgpr_count:     106
    .sgpr_spill_count: 100
    .symbol:         _Z4mega4Args.kd
    .uniform_work_group_size: 1
    .uses_dynamic_stack: false
    .vgpr_count:     256
    .vgpr_spill_count: 0
    .wavefront_size: 64
